# post_diff cache conversion rows split over all 2048 waves (quarter row each) instead of a 16-step extra iteration on the first 512 waves
# baseline (speedup 1.0000x reference)
.LBB0_961:
	s_andn2_b64 vcc, exec, s[0:1]
	s_cbranch_vccnz .LBB0_989
	v_mov_b32_e32 v1, v192
	v_mov_b32_e32 v2, v192
	s_add_u32 s10, s92, 0x11900000
	v_ashrrev_i32_e32 v0, 6, v2
	v_add_u32_e32 v26, s73, v0
	s_movk_i32 s0, 0x4800
	s_addc_u32 s11, s93, 0
	v_and_b32_e32 v60, 63, v1
	v_cmp_gt_i32_e32 vcc, s0, v26
	v_mov_b32_e32 v69, 0
	v_mov_b32_e32 v71, 0
	s_and_saveexec_b64 s[12:13], vcc
	s_cbranch_execz .LBB0_975
	v_lshrrev_b32_e32 v3, 6, v2
	v_lshlrev_b32_e32 v2, 3, v60
	v_and_b32_e32 v6, 4, v1
	v_cmp_eq_u32_e64 s[6:7], 0, v6
	v_and_b32_e32 v6, 8, v2
	v_cvt_f32_ubyte0_e32 v7, v6
	v_mul_f32_e32 v7, 0xbf549a78, v7
	v_exp_f32_e32 v61, v7
	v_or_b32_e32 v7, 1, v6
	v_cvt_f32_ubyte0_e32 v7, v7
	v_mul_f32_e32 v7, 0xbf549a78, v7
	v_exp_f32_e32 v62, v7
	v_or_b32_e32 v7, 2, v6
	v_cvt_f32_ubyte0_e32 v7, v7
	v_mul_f32_e32 v7, 0xbf549a78, v7
	v_exp_f32_e32 v63, v7
	v_or_b32_e32 v7, 3, v6
	v_cvt_f32_ubyte0_e32 v7, v7
	v_mul_f32_e32 v7, 0xbf549a78, v7
	v_exp_f32_e32 v64, v7
	v_or_b32_e32 v7, 4, v6
	v_cvt_f32_ubyte0_e32 v7, v7
	v_mul_f32_e32 v7, 0xbf549a78, v7
	v_exp_f32_e32 v65, v7
	v_or_b32_e32 v7, 5, v6
	v_cvt_f32_ubyte0_e32 v7, v7
	v_readlane_b32 s0, v254, 39
	v_mul_f32_e32 v7, 0xbf549a78, v7
	v_readlane_b32 s4, v254, 41
	v_lshlrev_b32_e32 v4, 4, v60
	v_mov_b32_e32 v5, v112
	v_readlane_b32 s1, v254, 40
	v_exp_f32_e32 v66, v7
	v_or_b32_e32 v7, 6, v6
	v_or_b32_e32 v6, 7, v6
	v_readlane_b32 s5, v254, 42
	v_lshl_add_u64 v[28:29], s[0:1], 0, v[4:5]
	v_cvt_f32_ubyte0_e32 v7, v7
	v_cvt_f32_ubyte0_e32 v6, v6
	v_lshl_add_u64 v[30:31], s[4:5], 0, v[4:5]
	v_mov_b64_e32 v[4:5], s[10:11]
	s_movk_i32 s0, 0x2200
	v_mul_f32_e32 v7, 0xbf549a78, v7
	v_mul_f32_e32 v6, 0xbf549a78, v6
	v_mad_u64_u32 v[32:33], s[0:1], v60, s0, v[4:5]
	v_exp_f32_e32 v67, v7
	v_exp_f32_e32 v68, v6
	v_and_b32_e32 v1, 2, v1
	v_readlane_b32 s0, v252, 57
	v_cmp_eq_u32_e64 s[8:9], 0, v1
	v_mov_b32_e32 v1, v112
	v_add_u32_e32 v34, s0, v0
	v_lshlrev_b32_e32 v0, 1, v60
	v_readlane_b32 s16, v253, 24
	v_lshl_add_u64 v[36:37], s[4:5], 0, v[0:1]
	v_lshlrev_b32_e32 v0, 2, v60
	v_readlane_b32 s24, v253, 32
	v_readlane_b32 s25, v253, 33
	v_readlane_b32 s26, v253, 34
	v_readlane_b32 s27, v253, 35
	v_add_u16_e32 v70, s73, v3
	v_lshl_add_u64 v[40:41], s[24:25], 0, v[0:1]
	v_lshl_add_u64 v[38:39], s[26:27], 0, v[0:1]
	v_mov_b32_e32 v69, 0
	s_mov_b64 s[14:15], 0
	v_lshlrev_b32_e32 v42, 2, v2
	v_mov_b32_e32 v71, 0
	v_readlane_b32 s17, v253, 25
	v_readlane_b32 s18, v253, 26
	v_readlane_b32 s19, v253, 27
	v_readlane_b32 s20, v253, 28
	v_readlane_b32 s21, v253, 29
	v_readlane_b32 s22, v253, 30
	v_readlane_b32 s23, v253, 31
	v_readlane_b32 s28, v253, 36
	v_readlane_b32 s29, v253, 37
	v_readlane_b32 s30, v253, 38
	v_readlane_b32 s31, v253, 39
	s_branch .LBB0_966

.LBB0_965:
	s_or_b64 exec, exec, s[16:17]
	v_readlane_b32 s0, v253, 3
	v_readlane_b32 s1, v253, 4
	s_movk_i32 s1, 0x47ff
	v_add_u32_e32 v26, s0, v26
	v_cmp_lt_i32_e32 vcc, s1, v26
	v_add_u32_e32 v34, s0, v34
	s_or_b64 s[14:15], vcc, s[14:15]
	v_add_u16_e32 v70, s0, v70
	s_andn2_b64 exec, exec, s[14:15]
	s_cbranch_execz .LBB0_974
.LBB0_966:
	s_movk_i32 s0, 0x3fff
	v_cmp_lt_i32_e32 vcc, s0, v26
	s_and_saveexec_b64 s[0:1], vcc
	s_xor_b64 s[16:17], exec, s[0:1]
	s_cbranch_execz .LBB0_969
	v_add_u32_e32 v7, 0xffffc000, v26
	v_lshrrev_b32_e32 v0, 10, v34
	v_lshrrev_b32_e32 v8, 10, v7
	v_mul_hi_u32_u24_e32 v1, 0x880000, v0
	v_mul_u32_u24_e32 v0, 0x880000, v0
	v_bfe_u32 v6, v34, 2, 8
	v_mul_hi_u32_u24_e32 v7, 0x1100, v8
	v_mul_u32_u24_e32 v8, 0x1100, v8
	v_mov_b32_e32 v35, v112
	v_lshl_or_b32 v0, v6, 1, v0
	v_and_b32_e32 v144, 3, v34
	v_mov_b32_e32 v145, 0x220000
	v_mad_u32_u24 v0, v144, v145, v0
	v_or_b32_e32 v6, v8, v6
	v_lshlrev_b64 v[4:5], 10, v[34:35]
	v_lshlrev_b64 v[6:7], 11, v[6:7]
	v_lshl_add_u32 v6, v144, 9, v6
	v_lshl_add_u64 v[0:1], v[32:33], 0, v[0:1]
	v_lshl_add_u64 v[2:3], v[38:39], 0, v[4:5]
	v_lshl_add_u64 v[4:5], v[40:41], 0, v[4:5]
	v_lshl_add_u64 v[6:7], v[36:37], 0, v[6:7]
	s_mov_b64 s[18:19], 0
	global_load_dword v12, v[4:5], off
	global_load_dword v13, v[2:3], off
	s_waitcnt vmcnt(0)
.LBB0_968:
	v_cvt_pk_bf16_f32 v8, v12, s0
	v_cvt_pk_bf16_f32 v14, v13, s0
	s_add_u32 s18, s18, 0x100
	s_addc_u32 s19, s19, 0
	s_cmpk_eq_i32 s18, 0x400
	s_cbranch_scc1 .Lpd_nopf
	v_lshl_add_u64 v[16:17], v[4:5], 0, s[18:19]
	global_load_dword v12, v[16:17], off
	v_lshl_add_u64 v[16:17], v[2:3], 0, s[18:19]
	global_load_dword v13, v[16:17], off
.Lpd_nopf:
	v_mov_b32_e32 v11, v192
	v_lshlrev_b32_e32 v9, 16, v8
	v_lshlrev_b32_e32 v11, 2, v11
	v_mul_f32_e32 v10, v9, v9
	v_bitop3_b32 v11, v11, s33, v203 bitop3:0x6c
	ds_bpermute_b32 v10, v11, v10
	s_waitcnt lgkmcnt(0)
	v_fmac_f32_e32 v10, v9, v9
	v_mov_b32_e32 v9, v192
	s_nop 0
	v_lshlrev_b32_e32 v9, 2, v9
	v_bitop3_b32 v9, v9, 64, v203 bitop3:0x6c
	ds_bpermute_b32 v9, v9, v10
	s_waitcnt lgkmcnt(0)
	v_add_f32_e32 v9, v10, v9
	v_mov_b32_e32 v10, v192
	s_nop 0
	v_lshlrev_b32_e32 v10, 2, v10
	v_bitop3_b32 v10, v10, 32, v203 bitop3:0x6c
	ds_bpermute_b32 v10, v10, v9
	s_waitcnt lgkmcnt(0)
	v_add_f32_e32 v9, v9, v10
	v_mov_b32_e32 v10, v192
	s_nop 0
	v_lshlrev_b32_e32 v10, 2, v10
	v_bitop3_b32 v10, v10, 16, v203 bitop3:0x6c
	ds_bpermute_b32 v10, v10, v9
	s_waitcnt lgkmcnt(0)
	v_add_f32_e32 v9, v9, v10
	v_mov_b32_e32 v10, v192
	s_nop 0
	v_lshlrev_b32_e32 v10, 2, v10
	v_bitop3_b32 v10, v10, 8, v203 bitop3:0x6c
	ds_bpermute_b32 v10, v10, v9
	s_waitcnt lgkmcnt(0)
	v_add_f32_e32 v9, v9, v10
	v_mov_b32_e32 v10, v192
	global_store_short v[6:7], v8, off
	v_lshlrev_b32_e32 v10, 2, v10
	v_bitop3_b32 v10, v10, 4, v203 bitop3:0x6c
	ds_bpermute_b32 v10, v10, v9
	v_lshl_add_u64 v[6:7], v[6:7], 0, s[94:95]
	s_waitcnt lgkmcnt(0)
	v_add_f32_e32 v9, v9, v10
	v_max_f32_e32 v10, v71, v71
	v_max_f32_e32 v71, v10, v9
	s_mov_b64 s[0:1], 0x88000
	global_store_short v[0:1], v14, off
	v_lshl_add_u64 v[0:1], v[0:1], 0, s[0:1]
	s_cmpk_lg_i32 s18, 0x400
	s_waitcnt vmcnt(2)
	s_cbranch_scc1 .LBB0_968
